# GEMM: first K-loop iteration peeled, its first MFMA into each accumulator takes C=0, so the 128 per-tile accumulator-zeroing moves are gone
# speedup vs baseline: 1.0060x; 1.0006x over previous
; #define LAS __attribute__((address_space(3)))
; #define S_STAGE(bufoff, gbase, voff) do { _Pragma("unroll") for (int _i = 0; _i < 2; ++_i) \
;     __builtin_amdgcn_global_load_lds((const unsigned*)((gbase) + (voff)[_i]), (LAS unsigned*)(lds + (bufoff) + ldsw + _i * 8192), 16, 0, 0); } while (0)
; #define S_LDA(dst, b, h) do { _Pragma("unroll") for (int m = 0; m < 4; ++m) _Pragma("unroll") for (int k = 0; k < 2; ++k) dst[m][k] = *(const LAS bf16x8*)(lds + S_SA(b, h) + aoff + m * 2048 + k * 1024); } while (0)
; #define S_LDB(dst, b, h) do { _Pragma("unroll") for (int n = 0; n < 2; ++n) _Pragma("unroll") for (int k = 0; k < 2; ++k) dst[n][k] = *(const LAS bf16x8*)(lds + S_SB(b, h) + boff + n * 2048 + k * 1024); } while (0)
; #define S_MMA(ai, bj, At_, Bt_) do { __builtin_amdgcn_s_setprio(1); _Pragma("unroll") for (int m = 0; m < 4; ++m) _Pragma("unroll") for (int n = 0; n < 2; ++n) _Pragma("unroll") for (int k = 0; k < 2; ++k) \
;     acc[ai][bj][m][n] = __builtin_amdgcn_mfma_f32_16x16x32_bf16(Bt_[n][k], At_[m][k], acc[ai][bj][m][n], 0, 0, 0); __builtin_amdgcn_s_setprio(0); } while (0)
; #define S_BAR __builtin_amdgcn_s_barrier()
; DI void gemm_phase(LAS unsigned char* lds, const GemmDesc& d, float* __restrict__ X) {
;     ...
;     int pm2 = 0, pn2 = 0; const bool has_next = tile_of(ui + 1, pm2, pn2);
;     const char* nA = has_next ? opA(pm2, pn2) : cA; const char* nB = has_next ? opB(pm2, pn2) : cB;
;     LAS float* rsl = (LAS float*)(lds + 131072 + (ui & 1) * 1024);
;     if (ui == 0 && d.epi != EPI_RESID) { if (ktid < 256) rsl[ktid] = row_rstd(d.P, d.np, d.inv_dim, pm * 256 + ktid); }
;     for (int t = 0; t < nt; t += 2) {
;       const bool last = (t == nt - 2);
;       const char* a1 = cA + (size_t)(t + 1) * kstepA;
;       const char* a2 = last ? nA : cA + (size_t)(t + 2) * kstepA; const char* b2 = last ? nB : cB + (size_t)(t + 2) * kstepB;
;       const char* a3 = a2 + kstepA; const char* b3 = b2 + kstepB;
;       S_LDB(B0, 0, 0); S_LDB(B1, 0, 1); S_SCHED; S_LDA(At, 0, 0); S_STAGE(S_SA(1, 1), a1 + hstepA, voffA);
;       S_WAIT_V(8); S_WAIT_L(0); S_BAR; S_MMA(0, 0, At, B0); S_MMA(0, 1, At, B1); S_BAR; S_SCHED;
;       S_LDA(At, 0, 1); S_STAGE(S_SB(0, 0), b2, voffB); S_STAGE(S_SB(0, 1), b2 + hstepB, voffB); S_STAGE(S_SA(0, 0), a2, voffA);
;       S_WAIT_V(8); S_WAIT_L(0); S_BAR; S_MMA(1, 0, At, B0); S_MMA(1, 1, At, B1); S_BAR; S_SCHED;
.LBB0_345:
	s_or_b64 exec, exec, s[78:79]
	s_add_u32 s20, s88, s27
	s_addc_u32 s21, s89, 0
	s_add_u32 s64, s90, 0x100
	s_addc_u32 s69, s91, 0
	s_mov_b64 s[90:91], 0
	s_nop 0
	s_add_u32 s14, s90, 1
	s_addc_u32 s15, s91, 0
	s_add_u32 vcc_lo, s90, 2
	s_addc_u32 vcc_hi, s91, 0
	s_lshl_b64 s[78:79], vcc, s8
	s_add_u32 s56, s88, s78
	s_addc_u32 s57, s89, s79
	s_cmp_eq_u32 s9, s90
	s_cselect_b32 s78, s12, s56
	s_cselect_b32 s79, s13, s57
	s_cselect_b32 s56, s86, s64
	s_cselect_b32 s57, s87, s69
	s_add_u32 s90, s78, s0
	s_addc_u32 s91, s79, 0
	s_add_i32 s93, 0, 0x10000
	v_add_u32_e32 v0, s93, v174
	s_add_i32 s6, 0, 0x14000
	ds_read_b128 v[130:133], v0
	ds_read_b128 v[134:137], v0 offset:1024
	ds_read_b128 v[138:141], v0 offset:2048
	ds_read_b128 v[142:145], v0 offset:3072
	v_add_u32_e32 v0, s6, v174
	ds_read_b128 v[158:161], v0
	ds_read_b128 v[162:165], v0 offset:1024
	ds_read_b128 v[166:169], v0 offset:2048
	ds_read_b128 v[170:173], v0 offset:3072
	s_lshl_b64 s[14:15], s[14:15], s8
	s_add_u32 s14, s20, s14
	s_addc_u32 s15, s21, s15
	v_lshl_add_u64 v[192:193], s[14:15], 0, v[148:149]
	s_add_i32 m0, s55, 0xc000
	ds_read_b128 v[180:183], v147
	ds_read_b128 v[184:187], v147 offset:1024
	ds_read_b128 v[188:191], v147 offset:2048
	ds_read_b128 v[196:199], v147 offset:3072
	ds_read_b128 v[200:203], v147 offset:4096
	ds_read_b128 v[216:219], v147 offset:5120
	ds_read_b128 v[222:225], v147 offset:6144
	ds_read_b128 v[226:229], v147 offset:7168
	global_load_lds_dwordx4 v[192:193], off
	v_lshl_add_u64 v[192:193], s[14:15], 0, v[152:153]
	s_add_i32 m0, s55, 0xe000
	s_nop 0
	global_load_lds_dwordx4 v[192:193], off
	s_waitcnt vmcnt(8)
	s_waitcnt lgkmcnt(0)
	s_setprio 1
	s_barrier
	v_mfma_f32_16x16x32_bf16 v[126:129], v[130:133], v[180:183], 0
	v_mfma_f32_16x16x32_bf16 v[122:125], v[138:141], v[180:183], 0
	v_mfma_f32_16x16x32_bf16 v[110:113], v[130:133], v[188:191], 0
	v_mfma_f32_16x16x32_bf16 v[106:109], v[138:141], v[188:191], 0
	v_mfma_f32_16x16x32_bf16 v[94:97], v[130:133], v[200:203], 0
	v_mfma_f32_16x16x32_bf16 v[90:93], v[138:141], v[200:203], 0
	v_mfma_f32_16x16x32_bf16 v[78:81], v[130:133], v[222:225], 0
	v_mfma_f32_16x16x32_bf16 v[74:77], v[138:141], v[222:225], 0
	v_mfma_f32_16x16x32_bf16 v[126:129], v[134:137], v[184:187], v[126:129]
	v_mfma_f32_16x16x32_bf16 v[122:125], v[142:145], v[184:187], v[122:125]
	v_mfma_f32_16x16x32_bf16 v[110:113], v[134:137], v[196:199], v[110:113]
	v_mfma_f32_16x16x32_bf16 v[106:109], v[142:145], v[196:199], v[106:109]
	v_mfma_f32_16x16x32_bf16 v[94:97], v[134:137], v[216:219], v[94:97]
	v_mfma_f32_16x16x32_bf16 v[90:93], v[142:145], v[216:219], v[90:93]
	v_mfma_f32_16x16x32_bf16 v[78:81], v[134:137], v[226:229], v[78:81]
	v_mfma_f32_16x16x32_bf16 v[74:77], v[142:145], v[226:229], v[74:77]
	v_mfma_f32_16x16x32_bf16 v[118:121], v[158:161], v[180:183], 0
	v_mfma_f32_16x16x32_bf16 v[114:117], v[166:169], v[180:183], 0
	v_mfma_f32_16x16x32_bf16 v[102:105], v[158:161], v[188:191], 0
	v_mfma_f32_16x16x32_bf16 v[98:101], v[166:169], v[188:191], 0
	v_mfma_f32_16x16x32_bf16 v[86:89], v[158:161], v[200:203], 0
	v_mfma_f32_16x16x32_bf16 v[82:85], v[166:169], v[200:203], 0
	v_mfma_f32_16x16x32_bf16 v[70:73], v[158:161], v[222:225], 0
	v_mfma_f32_16x16x32_bf16 v[66:69], v[166:169], v[222:225], 0
	v_mfma_f32_16x16x32_bf16 v[118:121], v[162:165], v[184:187], v[118:121]
	v_mfma_f32_16x16x32_bf16 v[114:117], v[170:173], v[184:187], v[114:117]
	v_mfma_f32_16x16x32_bf16 v[102:105], v[162:165], v[196:199], v[102:105]
	v_mfma_f32_16x16x32_bf16 v[98:101], v[170:173], v[196:199], v[98:101]
	v_mfma_f32_16x16x32_bf16 v[86:89], v[162:165], v[216:219], v[86:89]
	v_mfma_f32_16x16x32_bf16 v[82:85], v[170:173], v[216:219], v[82:85]
	v_mfma_f32_16x16x32_bf16 v[70:73], v[162:165], v[226:229], v[70:73]
	v_mfma_f32_16x16x32_bf16 v[66:69], v[170:173], v[226:229], v[66:69]
	s_barrier
	s_setprio 0
	s_add_i32 s14, s93, s51
	v_lshl_add_u64 v[192:193], s[56:57], 0, v[150:151]
	s_mov_b32 m0, s14
	ds_read_b128 v[180:183], v147 offset:16384
	ds_read_b128 v[184:187], v147 offset:17408
	ds_read_b128 v[188:191], v147 offset:18432
	ds_read_b128 v[196:199], v147 offset:19456
	ds_read_b128 v[200:203], v147 offset:20480
	ds_read_b128 v[216:219], v147 offset:21504
	ds_read_b128 v[222:225], v147 offset:22528
	ds_read_b128 v[226:229], v147 offset:23552
	global_load_lds_dwordx4 v[192:193], off
	s_add_i32 m0, s14, 0x2000
	s_add_u32 s14, s56, s50
	v_lshl_add_u64 v[230:231], s[56:57], 0, v[154:155]
	s_addc_u32 s15, s57, 0
	s_add_i32 s6, s6, s51
	global_load_lds_dwordx4 v[230:231], off
	v_lshl_add_u64 v[232:233], s[14:15], 0, v[150:151]
	s_mov_b32 m0, s6
	v_lshl_add_u64 v[234:235], s[14:15], 0, v[154:155]
	global_load_lds_dwordx4 v[232:233], off
	s_add_i32 m0, s6, 0x2000
	v_lshl_add_u64 v[236:237], s[78:79], 0, v[148:149]
	global_load_lds_dwordx4 v[234:235], off
	s_mov_b32 m0, s55
	s_nop 0
	global_load_lds_dwordx4 v[236:237], off
	v_lshl_add_u64 v[236:237], s[78:79], 0, v[152:153]
	s_mov_b32 m0, s58
	s_nop 0
	global_load_lds_dwordx4 v[236:237], off
	s_waitcnt vmcnt(8)
	s_waitcnt lgkmcnt(0)
	s_setprio 1
	s_barrier
; #define S_STAGE(bufoff, gbase, voff) do { _Pragma("unroll") for (int _i = 0; _i < 2; ++_i) \
;     __builtin_amdgcn_global_load_lds((const unsigned*)((gbase) + (voff)[_i]), (LAS unsigned*)(lds + (bufoff) + ldsw + _i * 8192), 16, 0, 0); } while (0)
; #define S_LDA(dst, b, h) do { _Pragma("unroll") for (int m = 0; m < 4; ++m) _Pragma("unroll") for (int k = 0; k < 2; ++k) dst[m][k] = *(const LAS bf16x8*)(lds + S_SA(b, h) + aoff + m * 2048 + k * 1024); } while (0)
; #define S_LDB(dst, b, h) do { _Pragma("unroll") for (int n = 0; n < 2; ++n) _Pragma("unroll") for (int k = 0; k < 2; ++k) dst[n][k] = *(const LAS bf16x8*)(lds + S_SB(b, h) + boff + n * 2048 + k * 1024); } while (0)
; #define S_MMA(ai, bj, At_, Bt_) do { __builtin_amdgcn_s_setprio(1); _Pragma("unroll") for (int m = 0; m < 4; ++m) _Pragma("unroll") for (int n = 0; n < 2; ++n) _Pragma("unroll") for (int k = 0; k < 2; ++k) \
;     acc[ai][bj][m][n] = __builtin_amdgcn_mfma_f32_16x16x32_bf16(Bt_[n][k], At_[m][k], acc[ai][bj][m][n], 0, 0, 0); __builtin_amdgcn_s_setprio(0); } while (0)
; #define S_WAIT_V(n) asm volatile("s_waitcnt vmcnt(" #n ")" ::: "memory")
; #define S_WAIT_L(n) asm volatile("s_waitcnt lgkmcnt(" #n ")" ::: "memory")
; #define S_BAR __builtin_amdgcn_s_barrier()
; #define S_SCHED __builtin_amdgcn_sched_barrier(0)
; DI void gemm_phase(LAS unsigned char* lds, const GemmDesc& d, float* __restrict__ X) {
;     ...
;       S_WAIT_V(8); S_WAIT_L(0); S_BAR; S_MMA(1, 0, At, B0); S_MMA(1, 1, At, B1); S_BAR; S_SCHED;
;       S_LDB(B0, 1, 0); S_LDB(B1, 1, 1); S_SCHED; S_LDA(At, 1, 0); S_STAGE(S_SA(0, 1), a2 + hstepA, voffA);
;       S_WAIT_V(8); S_WAIT_L(0); S_BAR; S_MMA(0, 0, At, B0); S_MMA(0, 1, At, B1); S_BAR; S_SCHED;
;       S_LDA(At, 1, 1); S_STAGE(S_SB(1, 0), b3, voffB); S_STAGE(S_SB(1, 1), b3 + hstepB, voffB); S_STAGE(S_SA(1, 0), a3, voffA);
	v_mfma_f32_16x16x32_bf16 v[62:65], v[130:133], v[180:183], 0
	v_mfma_f32_16x16x32_bf16 v[58:61], v[138:141], v[180:183], 0
	v_mfma_f32_16x16x32_bf16 v[46:49], v[130:133], v[188:191], 0
	v_mfma_f32_16x16x32_bf16 v[42:45], v[138:141], v[188:191], 0
	v_mfma_f32_16x16x32_bf16 v[30:33], v[130:133], v[200:203], 0
	v_mfma_f32_16x16x32_bf16 v[26:29], v[138:141], v[200:203], 0
	v_mfma_f32_16x16x32_bf16 v[14:17], v[130:133], v[222:225], 0
	v_mfma_f32_16x16x32_bf16 v[10:13], v[138:141], v[222:225], 0
	v_mfma_f32_16x16x32_bf16 v[62:65], v[134:137], v[184:187], v[62:65]
	v_mfma_f32_16x16x32_bf16 v[58:61], v[142:145], v[184:187], v[58:61]
	v_mfma_f32_16x16x32_bf16 v[46:49], v[134:137], v[196:199], v[46:49]
	v_mfma_f32_16x16x32_bf16 v[42:45], v[142:145], v[196:199], v[42:45]
	v_mfma_f32_16x16x32_bf16 v[30:33], v[134:137], v[216:219], v[30:33]
	v_mfma_f32_16x16x32_bf16 v[26:29], v[142:145], v[216:219], v[26:29]
	v_mfma_f32_16x16x32_bf16 v[14:17], v[134:137], v[226:229], v[14:17]
	v_mfma_f32_16x16x32_bf16 v[10:13], v[142:145], v[226:229], v[10:13]
	v_mfma_f32_16x16x32_bf16 v[54:57], v[158:161], v[180:183], 0
	v_mfma_f32_16x16x32_bf16 v[50:53], v[166:169], v[180:183], 0
	v_mfma_f32_16x16x32_bf16 v[38:41], v[158:161], v[188:191], 0
	v_mfma_f32_16x16x32_bf16 v[34:37], v[166:169], v[188:191], 0
	v_mfma_f32_16x16x32_bf16 v[22:25], v[158:161], v[200:203], 0
	v_mfma_f32_16x16x32_bf16 v[18:21], v[166:169], v[200:203], 0
	v_mfma_f32_16x16x32_bf16 v[6:9], v[158:161], v[222:225], 0
	v_mfma_f32_16x16x32_bf16 v[2:5], v[166:169], v[222:225], 0
	v_mfma_f32_16x16x32_bf16 v[54:57], v[162:165], v[184:187], v[54:57]
	v_mfma_f32_16x16x32_bf16 v[50:53], v[170:173], v[184:187], v[50:53]
	v_mfma_f32_16x16x32_bf16 v[38:41], v[162:165], v[196:199], v[38:41]
	v_mfma_f32_16x16x32_bf16 v[34:37], v[170:173], v[196:199], v[34:37]
	v_mfma_f32_16x16x32_bf16 v[22:25], v[162:165], v[216:219], v[22:25]
	v_mfma_f32_16x16x32_bf16 v[18:21], v[170:173], v[216:219], v[18:21]
	v_mfma_f32_16x16x32_bf16 v[6:9], v[162:165], v[226:229], v[6:9]
	v_mfma_f32_16x16x32_bf16 v[2:5], v[170:173], v[226:229], v[2:5]
	s_barrier
	s_setprio 0
	s_add_i32 s6, 0, 0x18000
	v_add_u32_e32 v0, s6, v174
	s_add_i32 s56, 0, 0x1c000
	ds_read_b128 v[130:133], v0
	ds_read_b128 v[134:137], v0 offset:1024
	ds_read_b128 v[138:141], v0 offset:2048
	ds_read_b128 v[142:145], v0 offset:3072
	v_add_u32_e32 v0, s56, v174
	ds_read_b128 v[158:161], v0
	ds_read_b128 v[162:165], v0 offset:1024
	ds_read_b128 v[166:169], v0 offset:2048
	ds_read_b128 v[170:173], v0 offset:3072
	s_add_u32 s14, s78, s27
	s_addc_u32 s15, s79, 0
	s_mov_b32 m0, s59
	v_lshl_add_u64 v[236:237], s[14:15], 0, v[148:149]
	ds_read_b128 v[180:183], v147 offset:32768
	ds_read_b128 v[184:187], v147 offset:33792
	ds_read_b128 v[188:191], v147 offset:34816
	ds_read_b128 v[196:199], v147 offset:35840
	ds_read_b128 v[200:203], v147 offset:36864
	ds_read_b128 v[216:219], v147 offset:37888
	ds_read_b128 v[222:225], v147 offset:38912
	ds_read_b128 v[226:229], v147 offset:39936
	global_load_lds_dwordx4 v[236:237], off
	v_lshl_add_u64 v[236:237], s[14:15], 0, v[152:153]
	s_mov_b32 m0, s83
	s_nop 0
	global_load_lds_dwordx4 v[236:237], off
	s_waitcnt vmcnt(8)
	s_waitcnt lgkmcnt(0)
	s_setprio 1
	s_barrier
	v_mfma_f32_16x16x32_bf16 v[126:129], v[130:133], v[180:183], v[126:129]
	v_mfma_f32_16x16x32_bf16 v[122:125], v[138:141], v[180:183], v[122:125]
	v_mfma_f32_16x16x32_bf16 v[110:113], v[130:133], v[188:191], v[110:113]
	v_mfma_f32_16x16x32_bf16 v[106:109], v[138:141], v[188:191], v[106:109]
	v_mfma_f32_16x16x32_bf16 v[94:97], v[130:133], v[200:203], v[94:97]
	v_mfma_f32_16x16x32_bf16 v[90:93], v[138:141], v[200:203], v[90:93]
	v_mfma_f32_16x16x32_bf16 v[78:81], v[130:133], v[222:225], v[78:81]
	v_mfma_f32_16x16x32_bf16 v[74:77], v[138:141], v[222:225], v[74:77]
	v_mfma_f32_16x16x32_bf16 v[126:129], v[134:137], v[184:187], v[126:129]
	v_mfma_f32_16x16x32_bf16 v[122:125], v[142:145], v[184:187], v[122:125]
	v_mfma_f32_16x16x32_bf16 v[110:113], v[134:137], v[196:199], v[110:113]
	v_mfma_f32_16x16x32_bf16 v[106:109], v[142:145], v[196:199], v[106:109]
	v_mfma_f32_16x16x32_bf16 v[94:97], v[134:137], v[216:219], v[94:97]
	v_mfma_f32_16x16x32_bf16 v[90:93], v[142:145], v[216:219], v[90:93]
	v_mfma_f32_16x16x32_bf16 v[78:81], v[134:137], v[226:229], v[78:81]
	v_mfma_f32_16x16x32_bf16 v[74:77], v[142:145], v[226:229], v[74:77]
	v_mfma_f32_16x16x32_bf16 v[118:121], v[158:161], v[180:183], v[118:121]
	v_mfma_f32_16x16x32_bf16 v[114:117], v[166:169], v[180:183], v[114:117]
	v_mfma_f32_16x16x32_bf16 v[102:105], v[158:161], v[188:191], v[102:105]
	v_mfma_f32_16x16x32_bf16 v[98:101], v[166:169], v[188:191], v[98:101]
	v_mfma_f32_16x16x32_bf16 v[86:89], v[158:161], v[200:203], v[86:89]
	v_mfma_f32_16x16x32_bf16 v[82:85], v[166:169], v[200:203], v[82:85]
	v_mfma_f32_16x16x32_bf16 v[70:73], v[158:161], v[222:225], v[70:73]
	v_mfma_f32_16x16x32_bf16 v[66:69], v[166:169], v[222:225], v[66:69]
	v_mfma_f32_16x16x32_bf16 v[118:121], v[162:165], v[184:187], v[118:121]
	v_mfma_f32_16x16x32_bf16 v[114:117], v[170:173], v[184:187], v[114:117]
	v_mfma_f32_16x16x32_bf16 v[102:105], v[162:165], v[196:199], v[102:105]
	v_mfma_f32_16x16x32_bf16 v[98:101], v[170:173], v[196:199], v[98:101]
	v_mfma_f32_16x16x32_bf16 v[86:89], v[162:165], v[216:219], v[86:89]
	v_mfma_f32_16x16x32_bf16 v[82:85], v[170:173], v[216:219], v[82:85]
	v_mfma_f32_16x16x32_bf16 v[70:73], v[162:165], v[226:229], v[70:73]
	v_mfma_f32_16x16x32_bf16 v[66:69], v[170:173], v[226:229], v[66:69]
	s_barrier
; #define S_STAGE(bufoff, gbase, voff) do { _Pragma("unroll") for (int _i = 0; _i < 2; ++_i) \
;     __builtin_amdgcn_global_load_lds((const unsigned*)((gbase) + (voff)[_i]), (LAS unsigned*)(lds + (bufoff) + ldsw + _i * 8192), 16, 0, 0); } while (0)
; #define S_LDA(dst, b, h) do { _Pragma("unroll") for (int m = 0; m < 4; ++m) _Pragma("unroll") for (int k = 0; k < 2; ++k) dst[m][k] = *(const LAS bf16x8*)(lds + S_SA(b, h) + aoff + m * 2048 + k * 1024); } while (0)
; #define S_MMA(ai, bj, At_, Bt_) do { __builtin_amdgcn_s_setprio(1); _Pragma("unroll") for (int m = 0; m < 4; ++m) _Pragma("unroll") for (int n = 0; n < 2; ++n) _Pragma("unroll") for (int k = 0; k < 2; ++k) \
;     acc[ai][bj][m][n] = __builtin_amdgcn_mfma_f32_16x16x32_bf16(Bt_[n][k], At_[m][k], acc[ai][bj][m][n], 0, 0, 0); __builtin_amdgcn_s_setprio(0); } while (0)
; #define S_WAIT_V(n) asm volatile("s_waitcnt vmcnt(" #n ")" ::: "memory")
; #define S_WAIT_L(n) asm volatile("s_waitcnt lgkmcnt(" #n ")" ::: "memory")
; #define S_BAR __builtin_amdgcn_s_barrier()
; #define S_SCHED __builtin_amdgcn_sched_barrier(0)
; DI void gemm_phase(LAS unsigned char* lds, const GemmDesc& d, float* __restrict__ X) {
;     ...
;       S_LDA(At, 1, 1); S_STAGE(S_SB(1, 0), b3, voffB); S_STAGE(S_SB(1, 1), b3 + hstepB, voffB); S_STAGE(S_SA(1, 0), a3, voffA);
;       S_WAIT_V(8); S_WAIT_L(0); S_BAR; S_MMA(1, 0, At, B0); S_MMA(1, 1, At, B1); S_BAR; S_SCHED;
	s_setprio 0
	s_add_i32 s6, s6, s51
	v_lshl_add_u64 v[192:193], v[192:193], 0, s[98:99]
	s_mov_b32 m0, s6
	ds_read_b128 v[180:183], v147 offset:49152
	ds_read_b128 v[184:187], v147 offset:50176
	ds_read_b128 v[188:191], v147 offset:51200
	ds_read_b128 v[196:199], v147 offset:52224
	ds_read_b128 v[200:203], v147 offset:53248
	ds_read_b128 v[216:219], v147 offset:54272
	ds_read_b128 v[222:225], v147 offset:55296
	ds_read_b128 v[226:229], v147 offset:56320
	global_load_lds_dwordx4 v[192:193], off
	v_lshl_add_u64 v[192:193], v[230:231], 0, s[98:99]
	s_add_i32 m0, s6, 0x2000
	s_add_i32 s6, s56, s51
	global_load_lds_dwordx4 v[192:193], off
	v_lshl_add_u64 v[192:193], v[232:233], 0, s[98:99]
	s_mov_b32 m0, s6
	s_nop 0
	global_load_lds_dwordx4 v[192:193], off
	v_lshl_add_u64 v[192:193], v[234:235], 0, s[98:99]
	s_add_i32 m0, s6, 0x2000
	s_nop 0
	global_load_lds_dwordx4 v[192:193], off
	v_lshl_add_u64 v[192:193], s[90:91], 0, v[148:149]
	s_mov_b32 m0, s82
	s_nop 0
	global_load_lds_dwordx4 v[192:193], off
	v_lshl_add_u64 v[192:193], s[90:91], 0, v[152:153]
	s_mov_b32 m0, s94
	s_nop 0
	global_load_lds_dwordx4 v[192:193], off
	s_waitcnt vmcnt(8)
	s_waitcnt lgkmcnt(0)
	s_setprio 1
	s_barrier
	v_mfma_f32_16x16x32_bf16 v[62:65], v[130:133], v[180:183], v[62:65]
	v_mfma_f32_16x16x32_bf16 v[58:61], v[138:141], v[180:183], v[58:61]
	v_mfma_f32_16x16x32_bf16 v[46:49], v[130:133], v[188:191], v[46:49]
	v_mfma_f32_16x16x32_bf16 v[42:45], v[138:141], v[188:191], v[42:45]
	v_mfma_f32_16x16x32_bf16 v[30:33], v[130:133], v[200:203], v[30:33]
	v_mfma_f32_16x16x32_bf16 v[26:29], v[138:141], v[200:203], v[26:29]
	v_mfma_f32_16x16x32_bf16 v[14:17], v[130:133], v[222:225], v[14:17]
	v_mfma_f32_16x16x32_bf16 v[10:13], v[138:141], v[222:225], v[10:13]
	v_mfma_f32_16x16x32_bf16 v[62:65], v[134:137], v[184:187], v[62:65]
	v_mfma_f32_16x16x32_bf16 v[58:61], v[142:145], v[184:187], v[58:61]
	v_mfma_f32_16x16x32_bf16 v[46:49], v[134:137], v[196:199], v[46:49]
	v_mfma_f32_16x16x32_bf16 v[42:45], v[142:145], v[196:199], v[42:45]
	v_mfma_f32_16x16x32_bf16 v[30:33], v[134:137], v[216:219], v[30:33]
	v_mfma_f32_16x16x32_bf16 v[26:29], v[142:145], v[216:219], v[26:29]
	v_mfma_f32_16x16x32_bf16 v[14:17], v[134:137], v[226:229], v[14:17]
	v_mfma_f32_16x16x32_bf16 v[10:13], v[142:145], v[226:229], v[10:13]
	v_mfma_f32_16x16x32_bf16 v[54:57], v[158:161], v[180:183], v[54:57]
	v_mfma_f32_16x16x32_bf16 v[50:53], v[166:169], v[180:183], v[50:53]
	v_mfma_f32_16x16x32_bf16 v[38:41], v[158:161], v[188:191], v[38:41]
	v_mfma_f32_16x16x32_bf16 v[34:37], v[166:169], v[188:191], v[34:37]
	v_mfma_f32_16x16x32_bf16 v[22:25], v[158:161], v[200:203], v[22:25]
	v_mfma_f32_16x16x32_bf16 v[18:21], v[166:169], v[200:203], v[18:21]
	v_mfma_f32_16x16x32_bf16 v[6:9], v[158:161], v[222:225], v[6:9]
	v_mfma_f32_16x16x32_bf16 v[2:5], v[166:169], v[222:225], v[2:5]
	v_mfma_f32_16x16x32_bf16 v[54:57], v[162:165], v[184:187], v[54:57]
	v_mfma_f32_16x16x32_bf16 v[50:53], v[170:173], v[184:187], v[50:53]
	v_mfma_f32_16x16x32_bf16 v[38:41], v[162:165], v[196:199], v[38:41]
	v_mfma_f32_16x16x32_bf16 v[34:37], v[170:173], v[196:199], v[34:37]
	v_mfma_f32_16x16x32_bf16 v[22:25], v[162:165], v[216:219], v[22:25]
	v_mfma_f32_16x16x32_bf16 v[18:21], v[170:173], v[216:219], v[18:21]
	v_mfma_f32_16x16x32_bf16 v[6:9], v[162:165], v[226:229], v[6:9]
	v_mfma_f32_16x16x32_bf16 v[2:5], v[170:173], v[226:229], v[2:5]
	s_barrier
	s_setprio 0
	s_add_u32 s64, s64, 0x100
	s_addc_u32 s69, s69, 0
	s_cmp_ge_u32 vcc_lo, s1
	s_mov_b64 s[90:91], vcc
